# mixer C: K-fragment LDS reads of a step issued together
# baseline (speedup 1.0000x reference)
; DI float fexp2(float x) { return __builtin_amdgcn_exp2f(x); }
; DI f32x16 mfma32(bf16x8 a, bf16x8 b, f32x16 c) { return __builtin_amdgcn_mfma_f32_32x32x16_bf16(a, b, c, 0, 0, 0); }
; DI void lds_fence() { asm volatile("s_waitcnt lgkmcnt(0)" ::: "memory"); __builtin_amdgcn_wave_barrier(); }
; DI float half_max(float v) { auto rr = __builtin_amdgcn_permlane32_swap(__float_as_uint(v), __float_as_uint(v), false, false); return fmaxf(__uint_as_float(rr[0]), __uint_as_float(rr[1])); }
; template <int DVB, bool MASKED = true>
; DI void attn_step32(const bf16* Kt, int KP, const bf16* Vt, int VP, const bf16x8 (&qf)[4], f32x16 (&o)[DVB], float& m, float& l, unsigned vmask, float c2, int lane) {
;   const int r32 = lane & 31, h = lane >> 5;
;   f32x16 s;
; #pragma unroll
;   for (int i = 0; i < 16; ++i) s[i] = 0.f;
; #pragma unroll
;   for (int t = 0; t < 4; ++t) { const bf16x8 kf = *(const bf16x8*)(Kt + r32 * KP + t * 16 + h * 8); s = mfma32(kf, qf[t], s); }
;   float mx = -INFINITY;
; #pragma unroll
;   for (int i = 0; i < 16; ++i) { if (MASKED) { s[i] = ((vmask >> i) & 1u) ? s[i] : -INFINITY; } mx = fmaxf(mx, s[i]); }
;   mx = half_max(mx);
;   const float mxs = mx * c2;
;   if (__any(mxs > m + 6.f)) {
;     const float mn = fmaxf(m, mxs);
;     const float alpha = fexp2(m - mn); l *= alpha;
; #pragma unroll
;     for (int d = 0; d < DVB; ++d)
; #pragma unroll
;       for (int i = 0; i < 16; ++i) o[d][i] *= alpha;
;     m = mn;
;   }
; template <int DVB>
; DI void band_run(const bf16* Kg, const bf16* Vg, int NP, int kbase, int nsteps, int dil, int roff, int qidx, int win,
;                  const bf16x8 (&qf)[4], f32x16 (&o)[DVB], float& m, float& l, float c2, bf16* Ks, bf16* Vs, int lane) {
;     ...
;   for (int j = 0; j < nsteps; ++j) {
;     lds_fence();
;     kv_store(R, Ks, Vs, lane);
;     lds_fence();
;     if (j + 1 < nsteps) band_load(R, Kg, Vg, NP, kbase + 32 * (j + 1), dil, roff, lane);
;     const int kb = kbase + 32 * j, lo_r = (qidx - win > 0 ? qidx - win : 0) - kb;
;     const unsigned vm = lane_rows(row_range_mask(lo_r, qidx - kb), h);
;     attn_step32<DVB>(Ks, WP, Vs, WP, qf, o, m, l, vm, c2, lane);
.LBB0_2620:
	v_max_i32_e32 v0, 0, v132
	v_lshl_or_b32 v0, v0, 4, v125
	v_lshlrev_b64 v[34:35], 13, v[0:1]
	s_waitcnt lgkmcnt(0)
	s_waitcnt vmcnt(7)
	ds_write_b128 v113, v[66:69]
	s_waitcnt vmcnt(6)
	ds_write_b128 v113, v[70:73] offset:4608
	s_waitcnt vmcnt(5)
	ds_write_b128 v113, v[74:77] offset:1152
	s_waitcnt vmcnt(4)
	ds_write_b128 v113, v[78:81] offset:5760
	s_waitcnt vmcnt(3)
	ds_write_b128 v113, v[82:85] offset:2304
	s_waitcnt vmcnt(2)
	ds_write_b128 v113, v[86:89] offset:6912
	s_waitcnt vmcnt(1)
	ds_write_b128 v113, v[94:97] offset:3456
	s_waitcnt vmcnt(0)
	ds_write_b128 v113, v[90:93] offset:8064
	v_or_b32_e32 v34, v34, v122
	s_waitcnt lgkmcnt(0)
	v_lshl_add_u64 v[38:39], v[110:111], 0, v[34:35]
	ds_read_b128 v[34:37], v114
	ds_read_b128 v[200:203], v114 offset:32
	ds_read_b128 v[204:207], v114 offset:64
	ds_read_b128 v[208:211], v114 offset:96
	v_max_i32_e32 v0, -8, v132
	v_lshl_add_u32 v0, v0, 4, v133
	global_load_dwordx4 v[66:69], v[38:39], off offset:1024
	global_load_dwordx4 v[70:73], v[38:39], off offset:2048
	v_lshlrev_b64 v[38:39], 13, v[0:1]
	v_or_b32_e32 v38, v38, v122
	v_lshl_add_u64 v[86:87], v[110:111], 0, v[38:39]
	s_waitcnt lgkmcnt(3)
	v_mfma_f32_32x32x16_bf16 v[34:49], v[34:37], v[62:65], 0
	global_load_dwordx4 v[74:77], v[86:87], off offset:1024
	global_load_dwordx4 v[78:81], v[86:87], off offset:2048
	v_max_i32_e32 v0, -16, v132
	v_lshl_add_u32 v0, v0, 4, v134
	v_lshlrev_b64 v[86:87], 13, v[0:1]
	v_max_i32_e32 v0, 0xffffffe8, v132
	v_lshl_add_u32 v0, v0, 4, v135
	s_waitcnt lgkmcnt(2)
	v_mfma_f32_32x32x16_bf16 v[34:49], v[200:203], v[58:61], v[34:49]
	v_lshlrev_b64 v[94:95], 13, v[0:1]
	v_or_b32_e32 v86, v86, v122
	v_or_b32_e32 v94, v94, v122
	v_lshl_add_u64 v[86:87], v[110:111], 0, v[86:87]
	v_lshl_add_u64 v[140:141], v[110:111], 0, v[94:95]
	global_load_dwordx4 v[82:85], v[86:87], off offset:1024
	s_nop 0
	global_load_dwordx4 v[86:89], v[86:87], off offset:2048
	s_waitcnt lgkmcnt(1)
	v_mfma_f32_32x32x16_bf16 v[34:49], v[204:207], v[54:57], v[34:49]
	global_load_dwordx4 v[94:97], v[140:141], off offset:1024
	global_load_dwordx4 v[90:93], v[140:141], off offset:2048
	v_add_u32_e32 v0, s15, v129
	v_max_i32_e32 v140, 0, v0
	v_lshlrev_b32_e64 v140, v140, -1
	v_cmp_gt_i32_e32 vcc, 32, v0
	s_waitcnt lgkmcnt(0)
	v_mfma_f32_32x32x16_bf16 v[34:49], v[208:211], v[50:53], v[34:49]
	v_cndmask_b32_e32 v0, 0, v140, vcc
	v_lshrrev_b32_e32 v140, v98, v0
	v_and_b32_e32 v0, 1, v140
	v_cmp_eq_u32_e32 vcc, 1, v0
	v_and_b32_e32 v0, 2, v140
	s_nop 6
	v_cndmask_b32_e32 v34, v123, v34, vcc
	v_cmp_ne_u32_e32 vcc, 0, v0
	v_and_b32_e32 v0, 4, v140
	s_nop 0
	v_cndmask_b32_e32 v35, v123, v35, vcc
	v_cmp_ne_u32_e32 vcc, 0, v0
	v_and_b32_e32 v0, 8, v140
	v_max3_f32 v137, v34, s2, v35
	v_cndmask_b32_e32 v136, v123, v36, vcc
	v_cmp_ne_u32_e32 vcc, 0, v0
	v_and_b32_e32 v36, 0x100, v140
	s_nop 0
	v_cndmask_b32_e32 v0, v123, v37, vcc
	v_cmp_ne_u32_e32 vcc, 0, v36
	v_and_b32_e32 v37, 0x200, v140
	v_max3_f32 v137, v137, v136, v0
	v_cndmask_b32_e32 v36, v123, v38, vcc
	v_cmp_ne_u32_e32 vcc, 0, v37
	v_and_b32_e32 v38, 0x400, v140
	s_nop 0
	v_cndmask_b32_e32 v37, v123, v39, vcc
	v_cmp_ne_u32_e32 vcc, 0, v38
	v_and_b32_e32 v39, 0x800, v140
	v_max3_f32 v137, v137, v36, v37
	v_cndmask_b32_e32 v38, v123, v40, vcc
	v_cmp_ne_u32_e32 vcc, 0, v39
	v_and_b32_e32 v40, 0x10000, v140
	s_nop 0
	v_cndmask_b32_e32 v39, v123, v41, vcc
	v_cmp_ne_u32_e32 vcc, 0, v40
	v_and_b32_e32 v41, 0x20000, v140
	v_max3_f32 v137, v137, v38, v39
	v_cndmask_b32_e32 v40, v123, v42, vcc
	v_cmp_ne_u32_e32 vcc, 0, v41
	v_and_b32_e32 v42, 0x40000, v140
	s_nop 0
	v_cndmask_b32_e32 v41, v123, v43, vcc
	v_cmp_ne_u32_e32 vcc, 0, v42
	v_and_b32_e32 v43, 0x80000, v140
	v_max3_f32 v137, v137, v40, v41
	v_cndmask_b32_e32 v42, v123, v44, vcc
	v_cmp_ne_u32_e32 vcc, 0, v43
	v_and_b32_e32 v44, 0x1000000, v140
	s_nop 0
	v_cndmask_b32_e32 v43, v123, v45, vcc
	v_cmp_ne_u32_e32 vcc, 0, v44
	v_and_b32_e32 v45, 0x2000000, v140
	v_max3_f32 v137, v137, v42, v43
	v_cndmask_b32_e32 v44, v123, v46, vcc
	v_cmp_ne_u32_e32 vcc, 0, v45
	v_and_b32_e32 v46, 0x4000000, v140
	s_nop 0
	v_cndmask_b32_e32 v45, v123, v47, vcc
	v_cmp_ne_u32_e32 vcc, 0, v46
	v_and_b32_e32 v47, 0x8000000, v140
	v_max3_f32 v137, v137, v44, v45
	v_cndmask_b32_e32 v46, v123, v48, vcc
	v_cmp_ne_u32_e32 vcc, 0, v47
	s_nop 1
	v_cndmask_b32_e32 v47, v123, v49, vcc
	v_max3_f32 v48, v137, v46, v47
	v_mov_b32_e32 v49, v48
	s_nop 1
	v_permlane32_swap_b32_e32 v48, v49
	v_max_f32_e32 v49, v49, v49
	v_max_f32_e32 v48, v48, v48
	v_max_f32_e32 v48, v48, v49
	v_mul_f32_e32 v48, 0x3e38aa3b, v48
	v_add_f32_e32 v49, 0x40c00000, v124
	v_cmp_gt_f32_e32 vcc, v48, v49
	s_cbranch_vccz .LBB0_2619
	v_max_f32_e32 v48, v48, v48
	v_max_f32_e32 v49, v124, v124
	v_max_f32_e32 v49, v49, v48
	v_sub_f32_e32 v48, v124, v49
	v_exp_f32_e32 v48, v48
	v_mov_b32_e32 v124, v49
	v_mul_f32_e32 v130, v130, v48
	v_pk_mul_f32 v[32:33], v[32:33], v[48:49] op_sel_hi:[1,0]
	v_pk_mul_f32 v[30:31], v[30:31], v[48:49] op_sel_hi:[1,0]
	v_pk_mul_f32 v[28:29], v[28:29], v[48:49] op_sel_hi:[1,0]
	v_pk_mul_f32 v[26:27], v[26:27], v[48:49] op_sel_hi:[1,0]
	v_pk_mul_f32 v[24:25], v[24:25], v[48:49] op_sel_hi:[1,0]
	v_pk_mul_f32 v[22:23], v[22:23], v[48:49] op_sel_hi:[1,0]
	v_pk_mul_f32 v[20:21], v[20:21], v[48:49] op_sel_hi:[1,0]
	v_pk_mul_f32 v[18:19], v[18:19], v[48:49] op_sel_hi:[1,0]
	v_pk_mul_f32 v[16:17], v[16:17], v[48:49] op_sel_hi:[1,0]
	v_pk_mul_f32 v[14:15], v[14:15], v[48:49] op_sel_hi:[1,0]
	v_pk_mul_f32 v[12:13], v[12:13], v[48:49] op_sel_hi:[1,0]
	v_pk_mul_f32 v[10:11], v[10:11], v[48:49] op_sel_hi:[1,0]
	v_pk_mul_f32 v[8:9], v[8:9], v[48:49] op_sel_hi:[1,0]
	v_pk_mul_f32 v[6:7], v[6:7], v[48:49] op_sel_hi:[1,0]
	v_pk_mul_f32 v[4:5], v[4:5], v[48:49] op_sel_hi:[1,0]
	v_pk_mul_f32 v[2:3], v[2:3], v[48:49] op_sel_hi:[1,0]
	s_branch .LBB0_2619

; DI float fexp2(float x) { return __builtin_amdgcn_exp2f(x); }
; DI f32x16 mfma32(bf16x8 a, bf16x8 b, f32x16 c) { return __builtin_amdgcn_mfma_f32_32x32x16_bf16(a, b, c, 0, 0, 0); }
; DI void lds_fence() { asm volatile("s_waitcnt lgkmcnt(0)" ::: "memory"); __builtin_amdgcn_wave_barrier(); }
; DI float half_max(float v) { auto rr = __builtin_amdgcn_permlane32_swap(__float_as_uint(v), __float_as_uint(v), false, false); return fmaxf(__uint_as_float(rr[0]), __uint_as_float(rr[1])); }
; template <int DVB, bool MASKED = true>
; DI void attn_step32(const bf16* Kt, int KP, const bf16* Vt, int VP, const bf16x8 (&qf)[4], f32x16 (&o)[DVB], float& m, float& l, unsigned vmask, float c2, int lane) {
;   const int r32 = lane & 31, h = lane >> 5;
;   f32x16 s;
; #pragma unroll
;   for (int i = 0; i < 16; ++i) s[i] = 0.f;
; #pragma unroll
;   for (int t = 0; t < 4; ++t) { const bf16x8 kf = *(const bf16x8*)(Kt + r32 * KP + t * 16 + h * 8); s = mfma32(kf, qf[t], s); }
;   float mx = -INFINITY;
; #pragma unroll
;   for (int i = 0; i < 16; ++i) { if (MASKED) { s[i] = ((vmask >> i) & 1u) ? s[i] : -INFINITY; } mx = fmaxf(mx, s[i]); }
;   mx = half_max(mx);
;   const float mxs = mx * c2;
;   if (__any(mxs > m + 6.f)) {
;     const float mn = fmaxf(m, mxs);
;     const float alpha = fexp2(m - mn); l *= alpha;
; #pragma unroll
;     for (int d = 0; d < DVB; ++d)
; #pragma unroll
;       for (int i = 0; i < 16; ++i) o[d][i] *= alpha;
;     m = mn;
;   }
; template <int DVB>
; DI void band_run(const bf16* Kg, const bf16* Vg, int NP, int kbase, int nsteps, int dil, int roff, int qidx, int win,
;                  const bf16x8 (&qf)[4], f32x16 (&o)[DVB], float& m, float& l, float c2, bf16* Ks, bf16* Vs, int lane) {
;     ...
;   for (int j = 0; j < nsteps; ++j) {
;     lds_fence();
;     kv_store(R, Ks, Vs, lane);
;     lds_fence();
;     if (j + 1 < nsteps) band_load(R, Kg, Vg, NP, kbase + 32 * (j + 1), dil, roff, lane);
;     const int kb = kbase + 32 * j, lo_r = (qidx - win > 0 ? qidx - win : 0) - kb;
;     const unsigned vm = lane_rows(row_range_mask(lo_r, qidx - kb), h);
;     attn_step32<DVB>(Ks, WP, Vs, WP, qf, o, m, l, vm, c2, lane);
.LBB0_2628:
	v_max_i32_e32 v0, 0, v135
	v_lshl_or_b32 v0, v0, 2, v133
	v_lshlrev_b64 v[34:35], 13, v[0:1]
	v_or_b32_e32 v34, v34, v122
	v_max_i32_e32 v0, -8, v135
	s_waitcnt lgkmcnt(0)
	s_waitcnt vmcnt(7)
	ds_write_b128 v113, v[66:69]
	s_waitcnt vmcnt(6)
	ds_write_b128 v113, v[70:73] offset:4608
	s_waitcnt vmcnt(5)
	ds_write_b128 v113, v[74:77] offset:1152
	s_waitcnt vmcnt(4)
	ds_write_b128 v113, v[78:81] offset:5760
	s_waitcnt vmcnt(3)
	ds_write_b128 v113, v[82:85] offset:2304
	s_waitcnt vmcnt(2)
	ds_write_b128 v113, v[86:89] offset:6912
	s_waitcnt vmcnt(1)
	ds_write_b128 v113, v[94:97] offset:3456
	s_waitcnt vmcnt(0)
	ds_write_b128 v113, v[90:93] offset:8064
	v_lshl_add_u64 v[34:35], v[110:111], 0, v[34:35]
	v_lshl_add_u32 v0, v0, 2, v136
	s_waitcnt lgkmcnt(0)
	global_load_dwordx4 v[66:69], v[34:35], off offset:1024
	global_load_dwordx4 v[70:73], v[34:35], off offset:2048
	v_lshlrev_b64 v[34:35], 13, v[0:1]
	v_max_i32_e32 v0, -16, v135
	v_lshl_add_u32 v0, v0, 2, v137
	v_lshlrev_b64 v[38:39], 13, v[0:1]
	v_max_i32_e32 v0, 0xffffffe8, v135
	v_lshl_add_u32 v0, v0, 2, v138
	v_lshlrev_b64 v[90:91], 13, v[0:1]
	v_or_b32_e32 v34, v34, v122
	v_or_b32_e32 v38, v38, v122
	v_or_b32_e32 v90, v90, v122
	v_lshl_add_u64 v[34:35], v[110:111], 0, v[34:35]
	v_lshl_add_u64 v[38:39], v[110:111], 0, v[38:39]
	v_lshl_add_u64 v[90:91], v[110:111], 0, v[90:91]
	global_load_dwordx4 v[74:77], v[34:35], off offset:1024
	global_load_dwordx4 v[78:81], v[34:35], off offset:2048
	ds_read_b128 v[34:37], v114
	ds_read_b128 v[200:203], v114 offset:32
	ds_read_b128 v[204:207], v114 offset:64
	ds_read_b128 v[208:211], v114 offset:96
	global_load_dwordx4 v[82:85], v[38:39], off offset:1024
	global_load_dwordx4 v[86:89], v[38:39], off offset:2048
	global_load_dwordx4 v[94:97], v[90:91], off offset:1024
	s_nop 0
	global_load_dwordx4 v[90:93], v[90:91], off offset:2048
	s_waitcnt lgkmcnt(3)
	v_mfma_f32_32x32x16_bf16 v[34:49], v[34:37], v[62:65], 0
	v_add_u32_e32 v139, s15, v119
	v_min_i32_e32 v148, 31, v139
	v_add_u32_e32 v0, s15, v134
	v_max_i32_e32 v0, 0, v0
	v_cmp_gt_i32_e32 vcc, 31, v139
	s_waitcnt lgkmcnt(2)
	v_mfma_f32_32x32x16_bf16 v[34:49], v[200:203], v[58:61], v[34:49]
	v_add_u32_e32 v140, 1, v148
	v_lshlrev_b32_e64 v140, v140, -1
	v_not_b32_e32 v149, v140
	v_cndmask_b32_e32 v139, -1, v149, vcc
	v_cmp_ge_i32_e32 vcc, v148, v0
	s_waitcnt lgkmcnt(1)
	v_mfma_f32_32x32x16_bf16 v[34:49], v[204:207], v[54:57], v[34:49]
	v_lshlrev_b32_e64 v144, v0, -1
	v_and_b32_e32 v139, v139, v144
	v_cndmask_b32_e32 v0, 0, v139, vcc
	v_lshrrev_b32_e32 v144, v98, v0
	v_and_b32_e32 v0, 1, v144
	v_cmp_eq_u32_e32 vcc, 1, v0
	v_and_b32_e32 v0, 2, v144
	s_waitcnt lgkmcnt(0)
	v_mfma_f32_32x32x16_bf16 v[34:49], v[208:211], v[50:53], v[34:49]
	s_nop 11
	v_cndmask_b32_e32 v34, v123, v34, vcc
	v_cmp_ne_u32_e32 vcc, 0, v0
	v_and_b32_e32 v0, 4, v144
	s_nop 0
	v_cndmask_b32_e32 v35, v123, v35, vcc
	v_cmp_ne_u32_e32 vcc, 0, v0
	v_and_b32_e32 v0, 8, v144
	v_max3_f32 v140, v34, s2, v35
	v_cndmask_b32_e32 v139, v123, v36, vcc
	v_cmp_ne_u32_e32 vcc, 0, v0
	v_and_b32_e32 v36, 0x100, v144
	s_nop 0
	v_cndmask_b32_e32 v0, v123, v37, vcc
	v_cmp_ne_u32_e32 vcc, 0, v36
	v_and_b32_e32 v37, 0x200, v144
	v_max3_f32 v140, v140, v139, v0
	v_cndmask_b32_e32 v36, v123, v38, vcc
	v_cmp_ne_u32_e32 vcc, 0, v37
	v_and_b32_e32 v38, 0x400, v144
	s_nop 0
	v_cndmask_b32_e32 v37, v123, v39, vcc
	v_cmp_ne_u32_e32 vcc, 0, v38
	v_and_b32_e32 v39, 0x800, v144
	v_max3_f32 v140, v140, v36, v37
	v_cndmask_b32_e32 v38, v123, v40, vcc
	v_cmp_ne_u32_e32 vcc, 0, v39
	v_and_b32_e32 v40, 0x10000, v144
	s_nop 0
	v_cndmask_b32_e32 v39, v123, v41, vcc
	v_cmp_ne_u32_e32 vcc, 0, v40
	v_and_b32_e32 v41, 0x20000, v144
	v_max3_f32 v140, v140, v38, v39
	v_cndmask_b32_e32 v40, v123, v42, vcc
	v_cmp_ne_u32_e32 vcc, 0, v41
	v_and_b32_e32 v42, 0x40000, v144
	s_nop 0
	v_cndmask_b32_e32 v41, v123, v43, vcc
	v_cmp_ne_u32_e32 vcc, 0, v42
	v_and_b32_e32 v43, 0x80000, v144
	v_max3_f32 v140, v140, v40, v41
	v_cndmask_b32_e32 v42, v123, v44, vcc
	v_cmp_ne_u32_e32 vcc, 0, v43
	v_and_b32_e32 v44, 0x1000000, v144
	s_nop 0
	v_cndmask_b32_e32 v43, v123, v45, vcc
	v_cmp_ne_u32_e32 vcc, 0, v44
	v_and_b32_e32 v45, 0x2000000, v144
	v_max3_f32 v140, v140, v42, v43
	v_cndmask_b32_e32 v44, v123, v46, vcc
	v_cmp_ne_u32_e32 vcc, 0, v45
	v_and_b32_e32 v46, 0x4000000, v144
	s_nop 0
	v_cndmask_b32_e32 v45, v123, v47, vcc
	v_cmp_ne_u32_e32 vcc, 0, v46
	v_and_b32_e32 v47, 0x8000000, v144
	v_max3_f32 v140, v140, v44, v45
	v_cndmask_b32_e32 v46, v123, v48, vcc
	v_cmp_ne_u32_e32 vcc, 0, v47
	s_nop 1
	v_cndmask_b32_e32 v47, v123, v49, vcc
	v_max3_f32 v48, v140, v46, v47
	v_mov_b32_e32 v49, v48
	s_nop 1
	v_permlane32_swap_b32_e32 v48, v49
	v_max_f32_e32 v49, v49, v49
	v_max_f32_e32 v48, v48, v48
	v_max_f32_e32 v48, v48, v49
	v_mul_f32_e32 v48, 0x3e38aa3b, v48
	v_add_f32_e32 v49, 0x40c00000, v124
	v_cmp_gt_f32_e32 vcc, v48, v49
	s_cbranch_vccz .LBB0_2627
	v_max_f32_e32 v48, v48, v48
	v_max_f32_e32 v49, v124, v124
	v_max_f32_e32 v49, v49, v48
	v_sub_f32_e32 v48, v124, v49
	v_exp_f32_e32 v48, v48
	v_mov_b32_e32 v124, v49
	v_mul_f32_e32 v130, v130, v48
	v_pk_mul_f32 v[32:33], v[32:33], v[48:49] op_sel_hi:[1,0]
	v_pk_mul_f32 v[30:31], v[30:31], v[48:49] op_sel_hi:[1,0]
	v_pk_mul_f32 v[28:29], v[28:29], v[48:49] op_sel_hi:[1,0]
	v_pk_mul_f32 v[26:27], v[26:27], v[48:49] op_sel_hi:[1,0]
	v_pk_mul_f32 v[24:25], v[24:25], v[48:49] op_sel_hi:[1,0]
	v_pk_mul_f32 v[22:23], v[22:23], v[48:49] op_sel_hi:[1,0]
	v_pk_mul_f32 v[20:21], v[20:21], v[48:49] op_sel_hi:[1,0]
	v_pk_mul_f32 v[18:19], v[18:19], v[48:49] op_sel_hi:[1,0]
	v_pk_mul_f32 v[16:17], v[16:17], v[48:49] op_sel_hi:[1,0]
	v_pk_mul_f32 v[14:15], v[14:15], v[48:49] op_sel_hi:[1,0]
	v_pk_mul_f32 v[12:13], v[12:13], v[48:49] op_sel_hi:[1,0]
	v_pk_mul_f32 v[10:11], v[10:11], v[48:49] op_sel_hi:[1,0]
	v_pk_mul_f32 v[8:9], v[8:9], v[48:49] op_sel_hi:[1,0]
	v_pk_mul_f32 v[6:7], v[6:7], v[48:49] op_sel_hi:[1,0]
	v_pk_mul_f32 v[4:5], v[4:5], v[48:49] op_sel_hi:[1,0]
	v_pk_mul_f32 v[2:3], v[2:3], v[48:49] op_sel_hi:[1,0]
	s_branch .LBB0_2627

; DI float fexp2(float x) { return __builtin_amdgcn_exp2f(x); }
; DI f32x16 mfma32(bf16x8 a, bf16x8 b, f32x16 c) { return __builtin_amdgcn_mfma_f32_32x32x16_bf16(a, b, c, 0, 0, 0); }
; DI void lds_fence() { asm volatile("s_waitcnt lgkmcnt(0)" ::: "memory"); __builtin_amdgcn_wave_barrier(); }
; DI float half_max(float v) { auto rr = __builtin_amdgcn_permlane32_swap(__float_as_uint(v), __float_as_uint(v), false, false); return fmaxf(__uint_as_float(rr[0]), __uint_as_float(rr[1])); }
; template <int DVB, bool MASKED = true>
; DI void attn_step32(const bf16* Kt, int KP, const bf16* Vt, int VP, const bf16x8 (&qf)[4], f32x16 (&o)[DVB], float& m, float& l, unsigned vmask, float c2, int lane) {
;   const int r32 = lane & 31, h = lane >> 5;
;   f32x16 s;
; #pragma unroll
;   for (int i = 0; i < 16; ++i) s[i] = 0.f;
; #pragma unroll
;   for (int t = 0; t < 4; ++t) { const bf16x8 kf = *(const bf16x8*)(Kt + r32 * KP + t * 16 + h * 8); s = mfma32(kf, qf[t], s); }
;   float mx = -INFINITY;
; #pragma unroll
;   for (int i = 0; i < 16; ++i) { if (MASKED) { s[i] = ((vmask >> i) & 1u) ? s[i] : -INFINITY; } mx = fmaxf(mx, s[i]); }
;   mx = half_max(mx);
;   const float mxs = mx * c2;
;   if (__any(mxs > m + 6.f)) {
;     const float mn = fmaxf(m, mxs);
;     const float alpha = fexp2(m - mn); l *= alpha;
; #pragma unroll
;     for (int d = 0; d < DVB; ++d)
; #pragma unroll
;       for (int i = 0; i < 16; ++i) o[d][i] *= alpha;
;     m = mn;
;   }
; template <int DVB>
; DI void band_run(const bf16* Kg, const bf16* Vg, int NP, int kbase, int nsteps, int dil, int roff, int qidx, int win,
;                  const bf16x8 (&qf)[4], f32x16 (&o)[DVB], float& m, float& l, float c2, bf16* Ks, bf16* Vs, int lane) {
;     ...
;   for (int j = 0; j < nsteps; ++j) {
;     lds_fence();
;     kv_store(R, Ks, Vs, lane);
;     lds_fence();
;     if (j + 1 < nsteps) band_load(R, Kg, Vg, NP, kbase + 32 * (j + 1), dil, roff, lane);
;     const int kb = kbase + 32 * j, lo_r = (qidx - win > 0 ? qidx - win : 0) - kb;
;     const unsigned vm = lane_rows(row_range_mask(lo_r, qidx - kb), h);
;     attn_step32<DVB>(Ks, WP, Vs, WP, qf, o, m, l, vm, c2, lane);
.LBB0_2635:
	v_max_i32_e32 v0, 0, v128
	v_lshlrev_b64 v[34:35], 13, v[0:1]
	v_or_b32_e32 v34, v34, v122
	v_max_i32_e32 v0, -8, v128
	s_waitcnt lgkmcnt(0)
	s_waitcnt vmcnt(7)
	ds_write_b128 v113, v[66:69]
	s_waitcnt vmcnt(6)
	ds_write_b128 v113, v[70:73] offset:4608
	s_waitcnt vmcnt(5)
	ds_write_b128 v113, v[74:77] offset:1152
	s_waitcnt vmcnt(4)
	ds_write_b128 v113, v[78:81] offset:5760
	s_waitcnt vmcnt(3)
	ds_write_b128 v113, v[82:85] offset:2304
	s_waitcnt vmcnt(2)
	ds_write_b128 v113, v[86:89] offset:6912
	s_waitcnt vmcnt(1)
	ds_write_b128 v113, v[94:97] offset:3456
	s_waitcnt vmcnt(0)
	ds_write_b128 v113, v[90:93] offset:8064
	v_lshl_add_u64 v[34:35], v[110:111], 0, v[34:35]
	v_add_u32_e32 v0, 8, v0
	s_waitcnt lgkmcnt(0)
	global_load_dwordx4 v[66:69], v[34:35], off offset:1024
	global_load_dwordx4 v[70:73], v[34:35], off offset:2048
	v_lshlrev_b64 v[34:35], 13, v[0:1]
	v_max_i32_e32 v0, -16, v128
	v_add_u32_e32 v0, 16, v0
	v_lshlrev_b64 v[38:39], 13, v[0:1]
	v_max_i32_e32 v0, 0xffffffe8, v128
	v_add_u32_e32 v0, 24, v0
	v_lshlrev_b64 v[90:91], 13, v[0:1]
	v_or_b32_e32 v34, v34, v122
	v_or_b32_e32 v38, v38, v122
	v_or_b32_e32 v90, v90, v122
	v_lshl_add_u64 v[34:35], v[110:111], 0, v[34:35]
	v_lshl_add_u64 v[38:39], v[110:111], 0, v[38:39]
	v_lshl_add_u64 v[90:91], v[110:111], 0, v[90:91]
	global_load_dwordx4 v[74:77], v[34:35], off offset:1024
	global_load_dwordx4 v[78:81], v[34:35], off offset:2048
	ds_read_b128 v[34:37], v114
	ds_read_b128 v[200:203], v114 offset:32
	ds_read_b128 v[204:207], v114 offset:64
	ds_read_b128 v[208:211], v114 offset:96
	global_load_dwordx4 v[82:85], v[38:39], off offset:1024
	global_load_dwordx4 v[86:89], v[38:39], off offset:2048
	global_load_dwordx4 v[94:97], v[90:91], off offset:1024
	s_nop 0
	global_load_dwordx4 v[90:93], v[90:91], off offset:2048
	s_waitcnt lgkmcnt(3)
	v_mfma_f32_32x32x16_bf16 v[34:49], v[34:37], v[62:65], 0
	v_add_u32_e32 v129, s15, v121
	v_min_i32_e32 v138, 31, v129
	v_add_u32_e32 v0, s15, v127
	v_max_i32_e32 v0, 0, v0
	v_cmp_gt_i32_e32 vcc, 31, v129
	s_waitcnt lgkmcnt(2)
	v_mfma_f32_32x32x16_bf16 v[34:49], v[200:203], v[58:61], v[34:49]
	v_add_u32_e32 v130, 1, v138
	v_lshlrev_b32_e64 v130, v130, -1
	v_not_b32_e32 v139, v130
	v_cndmask_b32_e32 v129, -1, v139, vcc
	v_cmp_ge_i32_e32 vcc, v138, v0
	s_waitcnt lgkmcnt(1)
	v_mfma_f32_32x32x16_bf16 v[34:49], v[204:207], v[54:57], v[34:49]
	v_lshlrev_b32_e64 v134, v0, -1
	v_and_b32_e32 v129, v129, v134
	v_cndmask_b32_e32 v0, 0, v129, vcc
	v_lshrrev_b32_e32 v134, v98, v0
	v_and_b32_e32 v0, 1, v134
	v_cmp_eq_u32_e32 vcc, 1, v0
	v_and_b32_e32 v0, 2, v134
	s_waitcnt lgkmcnt(0)
	v_mfma_f32_32x32x16_bf16 v[34:49], v[208:211], v[50:53], v[34:49]
	s_nop 11
	v_cndmask_b32_e32 v34, v123, v34, vcc
	v_cmp_ne_u32_e32 vcc, 0, v0
	v_and_b32_e32 v0, 4, v134
	s_nop 0
	v_cndmask_b32_e32 v35, v123, v35, vcc
	v_cmp_ne_u32_e32 vcc, 0, v0
	v_and_b32_e32 v0, 8, v134
	v_max3_f32 v130, v34, s2, v35
	v_cndmask_b32_e32 v129, v123, v36, vcc
	v_cmp_ne_u32_e32 vcc, 0, v0
	v_and_b32_e32 v36, 0x100, v134
	s_nop 0
	v_cndmask_b32_e32 v0, v123, v37, vcc
	v_cmp_ne_u32_e32 vcc, 0, v36
	v_and_b32_e32 v37, 0x200, v134
	v_max3_f32 v130, v130, v129, v0
	v_cndmask_b32_e32 v36, v123, v38, vcc
	v_cmp_ne_u32_e32 vcc, 0, v37
	v_and_b32_e32 v38, 0x400, v134
	s_nop 0
	v_cndmask_b32_e32 v37, v123, v39, vcc
	v_cmp_ne_u32_e32 vcc, 0, v38
	v_and_b32_e32 v39, 0x800, v134
	v_max3_f32 v130, v130, v36, v37
	v_cndmask_b32_e32 v38, v123, v40, vcc
	v_cmp_ne_u32_e32 vcc, 0, v39
	v_and_b32_e32 v40, 0x10000, v134
	s_nop 0
	v_cndmask_b32_e32 v39, v123, v41, vcc
	v_cmp_ne_u32_e32 vcc, 0, v40
	v_and_b32_e32 v41, 0x20000, v134
	v_max3_f32 v130, v130, v38, v39
	v_cndmask_b32_e32 v40, v123, v42, vcc
	v_cmp_ne_u32_e32 vcc, 0, v41
	v_and_b32_e32 v42, 0x40000, v134
	s_nop 0
	v_cndmask_b32_e32 v41, v123, v43, vcc
	v_cmp_ne_u32_e32 vcc, 0, v42
	v_and_b32_e32 v43, 0x80000, v134
	v_max3_f32 v130, v130, v40, v41
	v_cndmask_b32_e32 v42, v123, v44, vcc
	v_cmp_ne_u32_e32 vcc, 0, v43
	v_and_b32_e32 v44, 0x1000000, v134
	s_nop 0
	v_cndmask_b32_e32 v43, v123, v45, vcc
	v_cmp_ne_u32_e32 vcc, 0, v44
	v_and_b32_e32 v45, 0x2000000, v134
	v_max3_f32 v130, v130, v42, v43
	v_cndmask_b32_e32 v44, v123, v46, vcc
	v_cmp_ne_u32_e32 vcc, 0, v45
	v_and_b32_e32 v46, 0x4000000, v134
	s_nop 0
	v_cndmask_b32_e32 v45, v123, v47, vcc
	v_cmp_ne_u32_e32 vcc, 0, v46
	v_and_b32_e32 v47, 0x8000000, v134
	v_max3_f32 v130, v130, v44, v45
	v_cndmask_b32_e32 v46, v123, v48, vcc
	v_cmp_ne_u32_e32 vcc, 0, v47
	s_nop 1
	v_cndmask_b32_e32 v47, v123, v49, vcc
	v_max3_f32 v48, v130, v46, v47
	v_mov_b32_e32 v49, v48
	s_nop 1
	v_permlane32_swap_b32_e32 v48, v49
	v_max_f32_e32 v49, v49, v49
	v_max_f32_e32 v48, v48, v48
	v_max_f32_e32 v48, v48, v49
	v_mul_f32_e32 v48, 0x3e38aa3b, v48
	v_add_f32_e32 v49, 0x40c00000, v124
	v_cmp_gt_f32_e32 vcc, v48, v49
	s_cbranch_vccz .LBB0_2634
	v_max_f32_e32 v48, v48, v48
	v_max_f32_e32 v49, v124, v124
	v_max_f32_e32 v49, v49, v48
	v_sub_f32_e32 v48, v124, v49
	v_exp_f32_e32 v48, v48
	v_mov_b32_e32 v124, v49
	v_mul_f32_e32 v125, v125, v48
	v_pk_mul_f32 v[32:33], v[32:33], v[48:49] op_sel_hi:[1,0]
	v_pk_mul_f32 v[30:31], v[30:31], v[48:49] op_sel_hi:[1,0]
	v_pk_mul_f32 v[28:29], v[28:29], v[48:49] op_sel_hi:[1,0]
	v_pk_mul_f32 v[26:27], v[26:27], v[48:49] op_sel_hi:[1,0]
	v_pk_mul_f32 v[24:25], v[24:25], v[48:49] op_sel_hi:[1,0]
	v_pk_mul_f32 v[22:23], v[22:23], v[48:49] op_sel_hi:[1,0]
	v_pk_mul_f32 v[20:21], v[20:21], v[48:49] op_sel_hi:[1,0]
	v_pk_mul_f32 v[18:19], v[18:19], v[48:49] op_sel_hi:[1,0]
	v_pk_mul_f32 v[16:17], v[16:17], v[48:49] op_sel_hi:[1,0]
	v_pk_mul_f32 v[14:15], v[14:15], v[48:49] op_sel_hi:[1,0]
	v_pk_mul_f32 v[12:13], v[12:13], v[48:49] op_sel_hi:[1,0]
	v_pk_mul_f32 v[10:11], v[10:11], v[48:49] op_sel_hi:[1,0]
	v_pk_mul_f32 v[8:9], v[8:9], v[48:49] op_sel_hi:[1,0]
	v_pk_mul_f32 v[6:7], v[6:7], v[48:49] op_sel_hi:[1,0]
	v_pk_mul_f32 v[4:5], v[4:5], v[48:49] op_sel_hi:[1,0]
	v_pk_mul_f32 v[2:3], v[2:3], v[48:49] op_sel_hi:[1,0]
	s_branch .LBB0_2634
